# sc1 write-through also on rownorm output stores (8-byte)
# speedup vs baseline: 1.0825x; 1.0084x over previous
.LBB0_52:
	s_waitcnt lgkmcnt(2)
	v_add_f32_e32 v52, v52, v53
	v_fmamk_f32 v52, v52, 0x3a800000, v81
	v_mul_f32_e32 v53, 0x4b800000, v52
	v_cmp_gt_f32_e64 s[6:7], s22, v52
	s_nop 1
	v_cndmask_b32_e64 v52, v52, v53, s[6:7]
	v_rsq_f32_e32 v54, v52
	v_lshlrev_b64 v[52:53], 11, v[72:73]
	v_mul_f32_e32 v55, 0x45800000, v54
	v_cndmask_b32_e64 v54, v54, v55, s[6:7]
	v_pk_mul_f32 v[32:33], v[32:33], v[54:55] op_sel_hi:[1,0]
	v_pk_mul_f32 v[34:35], v[34:35], v[54:55] op_sel_hi:[1,0]
	v_pk_mul_f32 v[16:17], v[16:17], v[54:55] op_sel_hi:[1,0]
	v_pk_mul_f32 v[18:19], v[18:19], v[54:55] op_sel_hi:[1,0]
	v_cvt_pk_bf16_f32 v32, v32, v33
	v_cvt_pk_bf16_f32 v33, v34, v35
	v_lshl_add_u64 v[34:35], v[64:65], 0, v[52:53]
	v_cvt_pk_bf16_f32 v16, v16, v17
	v_cvt_pk_bf16_f32 v17, v18, v19
	global_store_dwordx2 v[34:35], v[16:17], off offset:512 sc1
	v_pk_mul_f32 v[16:17], v[20:21], v[54:55] op_sel_hi:[1,0]
	v_pk_mul_f32 v[18:19], v[22:23], v[54:55] op_sel_hi:[1,0]
	v_pk_mul_f32 v[12:13], v[12:13], v[54:55] op_sel_hi:[1,0]
	v_pk_mul_f32 v[14:15], v[14:15], v[54:55] op_sel_hi:[1,0]
	v_cvt_pk_bf16_f32 v16, v16, v17
	v_cvt_pk_bf16_f32 v17, v18, v19
	v_cvt_pk_bf16_f32 v12, v12, v13
	v_cvt_pk_bf16_f32 v13, v14, v15
	global_store_dwordx2 v[34:35], v[32:33], off sc1
	global_store_dwordx2 v[34:35], v[16:17], off offset:1024 sc1
	global_store_dwordx2 v[34:35], v[12:13], off offset:1536 sc1
	s_or_b64 exec, exec, s[10:11]
	s_and_saveexec_b64 s[10:11], s[8:9]
	s_cbranch_execz .LBB0_51
.LBB0_53:
	s_waitcnt lgkmcnt(1)
	v_add_f32_e32 v12, v50, v51
	v_fmamk_f32 v12, v12, 0x3a800000, v81
	v_mul_f32_e32 v13, 0x4b800000, v12
	v_cmp_gt_f32_e64 s[6:7], s22, v12
	s_nop 1
	v_cndmask_b32_e64 v12, v12, v13, s[6:7]
	v_rsq_f32_e32 v14, v12
	v_lshlrev_b64 v[12:13], 11, v[70:71]
	v_lshl_add_u64 v[12:13], v[64:65], 0, v[12:13]
	v_mul_f32_e32 v15, 0x45800000, v14
	v_cndmask_b32_e64 v14, v14, v15, s[6:7]
	v_pk_mul_f32 v[16:17], v[44:45], v[14:15] op_sel_hi:[1,0]
	v_pk_mul_f32 v[18:19], v[46:47], v[14:15] op_sel_hi:[1,0]
	v_cvt_pk_bf16_f32 v16, v16, v17
	v_cvt_pk_bf16_f32 v17, v18, v19
	global_store_dwordx2 v[12:13], v[16:17], off sc1
	v_pk_mul_f32 v[16:17], v[36:37], v[14:15] op_sel_hi:[1,0]
	v_pk_mul_f32 v[18:19], v[38:39], v[14:15] op_sel_hi:[1,0]
	v_cvt_pk_bf16_f32 v16, v16, v17
	v_cvt_pk_bf16_f32 v17, v18, v19
	global_store_dwordx2 v[12:13], v[16:17], off offset:512 sc1
	v_pk_mul_f32 v[16:17], v[40:41], v[14:15] op_sel_hi:[1,0]
	v_pk_mul_f32 v[18:19], v[42:43], v[14:15] op_sel_hi:[1,0]
	v_cvt_pk_bf16_f32 v16, v16, v17
	v_cvt_pk_bf16_f32 v17, v18, v19
	global_store_dwordx2 v[12:13], v[16:17], off offset:1024 sc1
	v_pk_mul_f32 v[16:17], v[28:29], v[14:15] op_sel_hi:[1,0]
	v_pk_mul_f32 v[14:15], v[30:31], v[14:15] op_sel_hi:[1,0]
	v_cvt_pk_bf16_f32 v16, v16, v17
	v_cvt_pk_bf16_f32 v17, v14, v15
	global_store_dwordx2 v[12:13], v[16:17], off offset:1536 sc1
	s_or_b64 exec, exec, s[10:11]
	s_and_saveexec_b64 s[6:7], s[4:5]
	s_cbranch_execz .LBB0_48
.LBB0_54:
	s_waitcnt lgkmcnt(0)
	v_add_f32_e32 v12, v48, v49
	v_fmamk_f32 v12, v12, 0x3a800000, v81
	v_mul_f32_e32 v13, 0x4b800000, v12
	v_cmp_gt_f32_e64 s[4:5], s22, v12
	s_nop 1
	v_cndmask_b32_e64 v12, v12, v13, s[4:5]
	v_rsq_f32_e32 v14, v12
	v_lshlrev_b64 v[12:13], 11, v[68:69]
	v_lshl_add_u64 v[12:13], v[64:65], 0, v[12:13]
	v_mul_f32_e32 v15, 0x45800000, v14
	v_cndmask_b32_e64 v14, v14, v15, s[4:5]
	v_pk_mul_f32 v[4:5], v[4:5], v[14:15] op_sel_hi:[1,0]
	v_pk_mul_f32 v[6:7], v[6:7], v[14:15] op_sel_hi:[1,0]
	v_cvt_pk_bf16_f32 v4, v4, v5
	v_cvt_pk_bf16_f32 v5, v6, v7
	v_pk_mul_f32 v[16:17], v[24:25], v[14:15] op_sel_hi:[1,0]
	v_pk_mul_f32 v[18:19], v[26:27], v[14:15] op_sel_hi:[1,0]
	global_store_dwordx2 v[12:13], v[4:5], off offset:512 sc1
	v_pk_mul_f32 v[4:5], v[8:9], v[14:15] op_sel_hi:[1,0]
	v_pk_mul_f32 v[6:7], v[10:11], v[14:15] op_sel_hi:[1,0]
	v_pk_mul_f32 v[0:1], v[0:1], v[14:15] op_sel_hi:[1,0]
	v_pk_mul_f32 v[2:3], v[2:3], v[14:15] op_sel_hi:[1,0]
	v_cvt_pk_bf16_f32 v16, v16, v17
	v_cvt_pk_bf16_f32 v17, v18, v19
	v_cvt_pk_bf16_f32 v4, v4, v5
	v_cvt_pk_bf16_f32 v5, v6, v7
	v_cvt_pk_bf16_f32 v0, v0, v1
	v_cvt_pk_bf16_f32 v1, v2, v3
	global_store_dwordx2 v[12:13], v[16:17], off sc1
	global_store_dwordx2 v[12:13], v[4:5], off offset:1024 sc1
	global_store_dwordx2 v[12:13], v[0:1], off offset:1536 sc1
	s_branch .LBB0_48

.LBB0_388:
	v_add_u32_e32 v0, s18, v58
	v_cmp_gt_i32_e64 s[8:9], s3, v0
	v_lshrrev_b32_e32 v69, 3, v58
	v_and_b32_e32 v59, 0x700, v66
	v_cndmask_b32_e64 v1, v58, v0, s[8:9]
	v_lshlrev_b32_e32 v2, 5, v1
	v_lshrrev_b32_e32 v3, 3, v1
	v_and_b32_e32 v2, 0x700, v2
	v_and_b32_e32 v3, 0xf8, v3
	v_and_b32_e32 v4, 0xfffff807, v1
	v_or3_b32 v2, v2, v4, v3
	v_cndmask_b32_e32 v56, v1, v2, vcc
	v_add_u32_e32 v2, s18, v0
	v_cmp_gt_i32_e64 s[4:5], s3, v2
	v_ashrrev_i32_e32 v57, 31, v56
	v_add_u32_e32 v68, s18, v2
	v_cndmask_b32_e64 v3, v58, v2, s[4:5]
	v_lshlrev_b32_e32 v0, 5, v3
	v_and_b32_e32 v4, 0x700, v0
	v_lshlrev_b64 v[0:1], 12, v[56:57]
	v_lshl_add_u64 v[0:1], v[50:51], 0, v[0:1]
	v_lshrrev_b32_e32 v5, 3, v3
	global_load_dwordx4 v[44:47], v[0:1], off
	global_load_dwordx4 v[40:43], v[0:1], off offset:1024
	v_and_b32_e32 v5, 0xf8, v5
	v_and_b32_e32 v6, 0xfffff807, v3
	global_load_dwordx4 v[36:39], v[0:1], off offset:2048
	global_load_dwordx4 v[32:35], v[0:1], off offset:3072
	v_or3_b32 v0, v4, v6, v5
	v_cndmask_b32_e32 v54, v3, v0, vcc
	v_ashrrev_i32_e32 v55, 31, v54
	v_lshlrev_b64 v[0:1], 12, v[54:55]
	v_lshl_add_u64 v[0:1], v[50:51], 0, v[0:1]
	v_cmp_gt_i32_e64 s[6:7], s3, v68
	global_load_dwordx4 v[28:31], v[0:1], off
	global_load_dwordx4 v[24:27], v[0:1], off offset:1024
	global_load_dwordx4 v[20:23], v[0:1], off offset:2048
	global_load_dwordx4 v[16:19], v[0:1], off offset:3072
	v_cndmask_b32_e64 v0, v58, v68, s[6:7]
	v_lshlrev_b32_e32 v1, 5, v0
	v_lshrrev_b32_e32 v2, 3, v0
	v_and_b32_e32 v3, 0xfffff807, v0
	v_and_b32_e32 v1, 0x700, v1
	v_and_b32_e32 v2, 0xf8, v2
	v_or3_b32 v1, v1, v3, v2
	v_cndmask_b32_e32 v52, v0, v1, vcc
	v_ashrrev_i32_e32 v53, 31, v52
	v_lshlrev_b64 v[0:1], 12, v[52:53]
	v_lshl_add_u64 v[0:1], v[50:51], 0, v[0:1]
	global_load_dwordx4 v[12:15], v[0:1], off
	global_load_dwordx4 v[8:11], v[0:1], off offset:1024
	global_load_dwordx4 v[4:7], v[0:1], off offset:2048
	s_nop 0
	global_load_dwordx4 v[0:3], v[0:1], off offset:3072
	s_waitcnt lgkmcnt(0)
	v_and_b32_e32 v70, 0xfffff807, v58
	v_and_b32_e32 v69, 0xf8, v69
	v_or3_b32 v59, v59, v70, v69
	v_cndmask_b32_e32 v58, v58, v59, vcc
	v_ashrrev_i32_e32 v59, 31, v58
	v_lshlrev_b64 v[70:71], 12, v[58:59]
	v_lshl_add_u64 v[70:71], v[50:51], 0, v[70:71]
	global_load_dwordx4 v[76:79], v[70:71], off
	global_load_dwordx4 v[80:83], v[70:71], off offset:1024
	global_load_dwordx4 v[84:87], v[70:71], off offset:2048
	global_load_dwordx4 v[88:91], v[70:71], off offset:3072
	v_lshlrev_b64 v[58:59], 11, v[58:59]
	v_lshl_add_u64 v[58:59], v[48:49], 0, v[58:59]
	s_waitcnt vmcnt(15)
	v_pk_mul_f32 v[70:71], v[44:45], v[44:45]
	s_waitcnt vmcnt(14)
	v_pk_mul_f32 v[74:75], v[40:41], v[40:41]
	v_pk_mul_f32 v[72:73], v[46:47], v[46:47]
	v_pk_mul_f32 v[92:93], v[42:43], v[42:43]
	s_waitcnt vmcnt(13)
	v_pk_mul_f32 v[94:95], v[36:37], v[36:37]
	v_add_f32_e32 v69, v74, v75
	v_add_f32_e32 v110, v70, v71
	v_pk_mul_f32 v[96:97], v[38:39], v[38:39]
	s_waitcnt vmcnt(12)
	v_pk_mul_f32 v[98:99], v[32:33], v[32:33]
	v_add_f32_e32 v111, v94, v95
	v_add_f32_e32 v69, v69, v92
	v_add_f32_e32 v72, v110, v72
	v_pk_mul_f32 v[100:101], v[34:35], v[34:35]
	v_add_f32_e32 v112, v98, v99
	v_add_f32_e32 v92, v111, v96
	v_add_f32_e32 v69, v69, v93
	v_add_f32_e32 v72, v72, v73
	v_add_f32_e32 v96, v112, v100
	v_add_f32_e32 v73, v92, v97
	v_add_f32_e32 v69, v72, v69
	v_add_f32_e32 v92, v96, v101
	v_add_f32_e32 v69, v69, v73
	s_waitcnt vmcnt(11)
	v_pk_mul_f32 v[70:71], v[28:29], v[28:29]
	s_waitcnt vmcnt(9)
	v_pk_mul_f32 v[102:103], v[20:21], v[20:21]
	v_add_f32_e32 v69, v69, v92
	v_add_f32_e32 v70, v70, v71
	v_add_f32_e32 v71, v102, v103
	ds_bpermute_b32 v103, v60, v69
	v_pk_mul_f32 v[74:75], v[30:31], v[30:31]
	v_pk_mul_f32 v[94:95], v[24:25], v[24:25]
	v_pk_mul_f32 v[98:99], v[26:27], v[26:27]
	v_add_f32_e32 v94, v94, v95
	v_add_f32_e32 v70, v70, v74
	v_pk_mul_f32 v[104:105], v[22:23], v[22:23]
	v_add_f32_e32 v72, v94, v98
	v_add_f32_e32 v70, v70, v75
	s_waitcnt vmcnt(6)
	v_pk_mul_f32 v[74:75], v[8:9], v[8:9]
	s_waitcnt lgkmcnt(0)
	v_add_f32_e32 v69, v69, v103
	v_add_f32_e32 v72, v72, v99
	v_add_f32_e32 v71, v71, v104
	v_add_f32_e32 v74, v74, v75
	ds_bpermute_b32 v75, v61, v69
	v_pk_mul_f32 v[106:107], v[16:17], v[16:17]
	v_add_f32_e32 v70, v70, v72
	v_add_f32_e32 v71, v71, v105
	v_pk_mul_f32 v[108:109], v[18:19], v[18:19]
	v_add_f32_e32 v70, v70, v71
	v_add_f32_e32 v71, v106, v107
	v_add_f32_e32 v71, v71, v108
	v_add_f32_e32 v71, v71, v109
	v_add_f32_e32 v102, v70, v71
	v_pk_mul_f32 v[70:71], v[12:13], v[12:13]
	s_waitcnt lgkmcnt(0)
	v_add_f32_e32 v69, v69, v75
	v_add_f32_e32 v70, v70, v71
	ds_bpermute_b32 v71, v62, v69
	v_pk_mul_f32 v[72:73], v[14:15], v[14:15]
	v_pk_mul_f32 v[92:93], v[10:11], v[10:11]
	s_waitcnt vmcnt(5)
	v_pk_mul_f32 v[94:95], v[4:5], v[4:5]
	v_pk_mul_f32 v[96:97], v[6:7], v[6:7]
	s_waitcnt lgkmcnt(0)
	v_add_f32_e32 v69, v69, v71
	v_add_f32_e32 v74, v74, v92
	v_add_f32_e32 v70, v70, v72
	v_add_f32_e32 v72, v94, v95
	ds_bpermute_b32 v71, v63, v69
	v_add_f32_e32 v74, v74, v93
	v_add_f32_e32 v70, v70, v73
	v_add_f32_e32 v72, v72, v96
	s_waitcnt vmcnt(4)
	v_pk_mul_f32 v[98:99], v[0:1], v[0:1]
	v_add_f32_e32 v70, v70, v74
	v_add_f32_e32 v72, v72, v97
	v_pk_mul_f32 v[100:101], v[2:3], v[2:3]
	v_add_f32_e32 v96, v70, v72
	v_add_f32_e32 v70, v98, v99
	s_waitcnt vmcnt(3)
	v_mov_b32_e32 v92, v77
	s_waitcnt vmcnt(2)
	v_mov_b32_e32 v93, v81
	v_add_f32_e32 v70, v70, v100
	v_mov_b32_e32 v74, v76
	v_mov_b32_e32 v75, v80
	v_pk_mul_f32 v[92:93], v[92:93], v[92:93]
	v_add_f32_e32 v97, v70, v101
	s_waitcnt lgkmcnt(0)
	v_add_f32_e32 v69, v69, v71
	v_mov_b32_e32 v70, v78
	v_mov_b32_e32 v71, v82
	v_pk_fma_f32 v[74:75], v[74:75], v[74:75], v[92:93]
	s_waitcnt vmcnt(1)
	v_mov_b32_e32 v94, v85
	s_waitcnt vmcnt(0)
	v_mov_b32_e32 v95, v89
	v_mov_b32_e32 v72, v79
	v_mov_b32_e32 v73, v83
	v_pk_fma_f32 v[70:71], v[70:71], v[70:71], v[74:75]
	v_mov_b32_e32 v92, v84
	v_mov_b32_e32 v93, v88
	v_pk_mul_f32 v[94:95], v[94:95], v[94:95]
	v_pk_fma_f32 v[70:71], v[72:73], v[72:73], v[70:71]
	v_mov_b32_e32 v72, v86
	v_mov_b32_e32 v73, v90
	v_pk_fma_f32 v[92:93], v[92:93], v[92:93], v[94:95]
	v_mov_b32_e32 v74, v87
	v_mov_b32_e32 v75, v91
	v_pk_fma_f32 v[72:73], v[72:73], v[72:73], v[92:93]
	v_add_f32_e32 v70, v70, v71
	v_pk_fma_f32 v[72:73], v[74:75], v[74:75], v[72:73]
	ds_bpermute_b32 v74, v60, v102
	v_add_f32_e32 v70, v70, v72
	v_add_f32_e32 v70, v70, v73
	ds_bpermute_b32 v71, v60, v70
	ds_bpermute_b32 v98, v64, v69
	s_waitcnt lgkmcnt(2)
	v_add_f32_e32 v74, v102, v74
	ds_bpermute_b32 v75, v61, v74
	v_add_f32_e32 v72, v96, v97
	s_waitcnt lgkmcnt(2)
	v_add_f32_e32 v70, v70, v71
	ds_bpermute_b32 v71, v61, v70
	s_waitcnt lgkmcnt(2)
	v_add_f32_e32 v73, v69, v98
	ds_bpermute_b32 v69, v60, v72
	s_waitcnt lgkmcnt(2)
	v_add_f32_e32 v74, v74, v75
	ds_bpermute_b32 v75, v62, v74
	s_waitcnt lgkmcnt(2)
	v_add_f32_e32 v70, v70, v71
	ds_bpermute_b32 v71, v62, v70
	s_waitcnt lgkmcnt(2)
	v_add_f32_e32 v69, v72, v69
	ds_bpermute_b32 v72, v61, v69
	s_waitcnt lgkmcnt(2)
	v_add_f32_e32 v74, v74, v75
	ds_bpermute_b32 v75, v63, v74
	s_waitcnt lgkmcnt(2)
	v_add_f32_e32 v70, v70, v71
	ds_bpermute_b32 v71, v63, v70
	s_waitcnt lgkmcnt(2)
	v_add_f32_e32 v69, v69, v72
	ds_bpermute_b32 v72, v62, v69
	s_waitcnt lgkmcnt(2)
	v_add_f32_e32 v75, v74, v75
	ds_bpermute_b32 v92, v64, v75
	s_waitcnt lgkmcnt(2)
	v_add_f32_e32 v70, v70, v71
	ds_bpermute_b32 v71, v64, v70
	s_waitcnt lgkmcnt(2)
	v_add_f32_e32 v69, v69, v72
	ds_bpermute_b32 v72, v63, v69
	ds_bpermute_b32 v74, v65, v73
	s_waitcnt lgkmcnt(2)
	v_add_f32_e32 v70, v70, v71
	ds_bpermute_b32 v94, v65, v70
	v_add_f32_e32 v71, v75, v92
	s_waitcnt lgkmcnt(2)
	v_add_f32_e32 v69, v69, v72
	ds_bpermute_b32 v93, v64, v69
	ds_bpermute_b32 v72, v65, v71
	s_waitcnt lgkmcnt(2)
	v_add_f32_e32 v70, v70, v94
	v_fmamk_f32 v70, v70, 0x3a800000, v67
	v_mul_f32_e32 v75, 0x4b800000, v70
	v_cmp_gt_f32_e64 s[10:11], s22, v70
	s_waitcnt lgkmcnt(1)
	v_add_f32_e32 v69, v69, v93
	v_cndmask_b32_e64 v70, v70, v75, s[10:11]
	v_rsq_f32_e32 v75, v70
	ds_bpermute_b32 v70, v65, v69
	v_mul_f32_e32 v92, 0x45800000, v75
	v_cndmask_b32_e64 v92, v75, v92, s[10:11]
	v_pk_mul_f32 v[76:77], v[76:77], v[92:93] op_sel_hi:[1,0]
	v_pk_mul_f32 v[78:79], v[78:79], v[92:93] op_sel_hi:[1,0]
	v_cvt_pk_bf16_f32 v76, v76, v77
	v_cvt_pk_bf16_f32 v77, v78, v79
	global_store_dwordx2 v[58:59], v[76:77], off sc1
	v_pk_mul_f32 v[76:77], v[80:81], v[92:93] op_sel_hi:[1,0]
	v_pk_mul_f32 v[78:79], v[82:83], v[92:93] op_sel_hi:[1,0]
	v_cvt_pk_bf16_f32 v76, v76, v77
	v_cvt_pk_bf16_f32 v77, v78, v79
	global_store_dwordx2 v[58:59], v[76:77], off offset:512 sc1
	v_pk_mul_f32 v[76:77], v[84:85], v[92:93] op_sel_hi:[1,0]
	v_pk_mul_f32 v[78:79], v[86:87], v[92:93] op_sel_hi:[1,0]
	v_cvt_pk_bf16_f32 v76, v76, v77
	v_cvt_pk_bf16_f32 v77, v78, v79
	global_store_dwordx2 v[58:59], v[76:77], off offset:1024 sc1
	v_pk_mul_f32 v[76:77], v[88:89], v[92:93] op_sel_hi:[1,0]
	v_pk_mul_f32 v[78:79], v[90:91], v[92:93] op_sel_hi:[1,0]
	v_cvt_pk_bf16_f32 v76, v76, v77
	v_cvt_pk_bf16_f32 v77, v78, v79
	global_store_dwordx2 v[58:59], v[76:77], off offset:1536 sc1
	s_and_saveexec_b64 s[10:11], s[8:9]
	s_cbranch_execnz .LBB0_391
	s_or_b64 exec, exec, s[10:11]
	s_and_saveexec_b64 s[8:9], s[4:5]
	s_cbranch_execnz .LBB0_392

.LBB0_391:
	v_add_f32_e32 v58, v73, v74
	v_fmamk_f32 v58, v58, 0x3a800000, v67
	v_mul_f32_e32 v59, 0x4b800000, v58
	v_cmp_gt_f32_e64 s[8:9], s22, v58
	v_lshlrev_b64 v[56:57], 11, v[56:57]
	s_nop 0
	v_cndmask_b32_e64 v58, v58, v59, s[8:9]
	v_rsq_f32_e32 v58, v58
	s_nop 0
	v_mul_f32_e32 v59, 0x45800000, v58
	v_cndmask_b32_e64 v58, v58, v59, s[8:9]
	v_pk_mul_f32 v[44:45], v[44:45], v[58:59] op_sel_hi:[1,0]
	v_pk_mul_f32 v[46:47], v[46:47], v[58:59] op_sel_hi:[1,0]
	v_pk_mul_f32 v[40:41], v[40:41], v[58:59] op_sel_hi:[1,0]
	v_pk_mul_f32 v[42:43], v[42:43], v[58:59] op_sel_hi:[1,0]
	v_pk_mul_f32 v[36:37], v[36:37], v[58:59] op_sel_hi:[1,0]
	v_pk_mul_f32 v[38:39], v[38:39], v[58:59] op_sel_hi:[1,0]
	v_pk_mul_f32 v[32:33], v[32:33], v[58:59] op_sel_hi:[1,0]
	v_pk_mul_f32 v[34:35], v[34:35], v[58:59] op_sel_hi:[1,0]
	v_cvt_pk_bf16_f32 v44, v44, v45
	v_cvt_pk_bf16_f32 v45, v46, v47
	v_lshl_add_u64 v[46:47], v[48:49], 0, v[56:57]
	v_cvt_pk_bf16_f32 v40, v40, v41
	v_cvt_pk_bf16_f32 v41, v42, v43
	v_cvt_pk_bf16_f32 v36, v36, v37
	v_cvt_pk_bf16_f32 v37, v38, v39
	v_cvt_pk_bf16_f32 v32, v32, v33
	v_cvt_pk_bf16_f32 v33, v34, v35
	global_store_dwordx2 v[46:47], v[44:45], off sc1
	global_store_dwordx2 v[46:47], v[40:41], off offset:512 sc1
	global_store_dwordx2 v[46:47], v[36:37], off offset:1024 sc1
	global_store_dwordx2 v[46:47], v[32:33], off offset:1536 sc1
	s_or_b64 exec, exec, s[10:11]
	s_and_saveexec_b64 s[8:9], s[4:5]
	s_cbranch_execz .LBB0_390
.LBB0_392:
	s_waitcnt lgkmcnt(1)
	v_add_f32_e32 v32, v71, v72
	v_fmamk_f32 v32, v32, 0x3a800000, v67
	v_mul_f32_e32 v33, 0x4b800000, v32
	v_cmp_gt_f32_e64 s[4:5], s22, v32
	s_nop 1
	v_cndmask_b32_e64 v32, v32, v33, s[4:5]
	v_rsq_f32_e32 v34, v32
	v_lshlrev_b64 v[32:33], 11, v[54:55]
	v_mul_f32_e32 v35, 0x45800000, v34
	v_cndmask_b32_e64 v34, v34, v35, s[4:5]
	v_pk_mul_f32 v[28:29], v[28:29], v[34:35] op_sel_hi:[1,0]
	v_pk_mul_f32 v[30:31], v[30:31], v[34:35] op_sel_hi:[1,0]
	v_pk_mul_f32 v[24:25], v[24:25], v[34:35] op_sel_hi:[1,0]
	v_pk_mul_f32 v[26:27], v[26:27], v[34:35] op_sel_hi:[1,0]
	v_pk_mul_f32 v[20:21], v[20:21], v[34:35] op_sel_hi:[1,0]
	v_pk_mul_f32 v[22:23], v[22:23], v[34:35] op_sel_hi:[1,0]
	v_pk_mul_f32 v[16:17], v[16:17], v[34:35] op_sel_hi:[1,0]
	v_pk_mul_f32 v[18:19], v[18:19], v[34:35] op_sel_hi:[1,0]
	v_cvt_pk_bf16_f32 v28, v28, v29
	v_cvt_pk_bf16_f32 v29, v30, v31
	v_lshl_add_u64 v[30:31], v[48:49], 0, v[32:33]
	v_cvt_pk_bf16_f32 v24, v24, v25
	v_cvt_pk_bf16_f32 v25, v26, v27
	v_cvt_pk_bf16_f32 v20, v20, v21
	v_cvt_pk_bf16_f32 v21, v22, v23
	v_cvt_pk_bf16_f32 v16, v16, v17
	v_cvt_pk_bf16_f32 v17, v18, v19
	global_store_dwordx2 v[30:31], v[28:29], off sc1
	global_store_dwordx2 v[30:31], v[24:25], off offset:512 sc1
	global_store_dwordx2 v[30:31], v[20:21], off offset:1024 sc1
	global_store_dwordx2 v[30:31], v[16:17], off offset:1536 sc1
	s_or_b64 exec, exec, s[8:9]
	s_and_saveexec_b64 s[8:9], s[6:7]
	s_cbranch_execz .LBB0_387
.LBB0_393:
	s_waitcnt lgkmcnt(0)
	v_add_f32_e32 v16, v69, v70
	v_fmamk_f32 v16, v16, 0x3a800000, v67
	v_mul_f32_e32 v17, 0x4b800000, v16
	v_cmp_gt_f32_e64 s[4:5], s22, v16
	s_nop 1
	v_cndmask_b32_e64 v16, v16, v17, s[4:5]
	v_rsq_f32_e32 v18, v16
	v_lshlrev_b64 v[16:17], 11, v[52:53]
	v_mul_f32_e32 v19, 0x45800000, v18
	v_cndmask_b32_e64 v18, v18, v19, s[4:5]
	v_pk_mul_f32 v[12:13], v[12:13], v[18:19] op_sel_hi:[1,0]
	v_pk_mul_f32 v[14:15], v[14:15], v[18:19] op_sel_hi:[1,0]
	v_pk_mul_f32 v[8:9], v[8:9], v[18:19] op_sel_hi:[1,0]
	v_pk_mul_f32 v[10:11], v[10:11], v[18:19] op_sel_hi:[1,0]
	v_pk_mul_f32 v[4:5], v[4:5], v[18:19] op_sel_hi:[1,0]
	v_pk_mul_f32 v[6:7], v[6:7], v[18:19] op_sel_hi:[1,0]
	v_pk_mul_f32 v[0:1], v[0:1], v[18:19] op_sel_hi:[1,0]
	v_pk_mul_f32 v[2:3], v[2:3], v[18:19] op_sel_hi:[1,0]
	v_cvt_pk_bf16_f32 v12, v12, v13
	v_cvt_pk_bf16_f32 v13, v14, v15
	v_lshl_add_u64 v[14:15], v[48:49], 0, v[16:17]
	v_cvt_pk_bf16_f32 v8, v8, v9
	v_cvt_pk_bf16_f32 v9, v10, v11
	v_cvt_pk_bf16_f32 v4, v4, v5
	v_cvt_pk_bf16_f32 v5, v6, v7
	v_cvt_pk_bf16_f32 v0, v0, v1
	v_cvt_pk_bf16_f32 v1, v2, v3
	global_store_dwordx2 v[14:15], v[12:13], off sc1
	global_store_dwordx2 v[14:15], v[8:9], off offset:512 sc1
	global_store_dwordx2 v[14:15], v[4:5], off offset:1024 sc1
	global_store_dwordx2 v[14:15], v[0:1], off offset:1536 sc1
	s_branch .LBB0_387

.LBB0_868:
	v_add_u32_e32 v0, s16, v58
	v_cmp_gt_i32_e64 s[6:7], s3, v0
	v_lshrrev_b32_e32 v69, 3, v58
	v_and_b32_e32 v59, 0x700, v66
	v_cndmask_b32_e64 v1, v58, v0, s[6:7]
	v_lshlrev_b32_e32 v2, 5, v1
	v_lshrrev_b32_e32 v3, 3, v1
	v_and_b32_e32 v2, 0x700, v2
	v_and_b32_e32 v3, 0xf8, v3
	v_and_b32_e32 v4, 0xfffff807, v1
	v_or3_b32 v2, v2, v4, v3
	v_cndmask_b32_e32 v56, v1, v2, vcc
	v_add_u32_e32 v2, s16, v0
	v_cmp_gt_i32_e64 s[0:1], s3, v2
	v_ashrrev_i32_e32 v57, 31, v56
	v_add_u32_e32 v68, s16, v2
	v_cndmask_b32_e64 v3, v58, v2, s[0:1]
	v_lshlrev_b32_e32 v0, 5, v3
	v_and_b32_e32 v4, 0x700, v0
	v_lshlrev_b64 v[0:1], 12, v[56:57]
	v_lshl_add_u64 v[0:1], v[50:51], 0, v[0:1]
	v_lshrrev_b32_e32 v5, 3, v3
	global_load_dwordx4 v[44:47], v[0:1], off
	global_load_dwordx4 v[40:43], v[0:1], off offset:1024
	v_and_b32_e32 v5, 0xf8, v5
	v_and_b32_e32 v6, 0xfffff807, v3
	global_load_dwordx4 v[36:39], v[0:1], off offset:2048
	global_load_dwordx4 v[32:35], v[0:1], off offset:3072
	v_or3_b32 v0, v4, v6, v5
	v_cndmask_b32_e32 v54, v3, v0, vcc
	v_ashrrev_i32_e32 v55, 31, v54
	v_lshlrev_b64 v[0:1], 12, v[54:55]
	v_lshl_add_u64 v[0:1], v[50:51], 0, v[0:1]
	v_cmp_gt_i32_e64 s[4:5], s3, v68
	global_load_dwordx4 v[28:31], v[0:1], off
	global_load_dwordx4 v[24:27], v[0:1], off offset:1024
	global_load_dwordx4 v[20:23], v[0:1], off offset:2048
	global_load_dwordx4 v[16:19], v[0:1], off offset:3072
	v_cndmask_b32_e64 v0, v58, v68, s[4:5]
	v_lshlrev_b32_e32 v1, 5, v0
	v_lshrrev_b32_e32 v2, 3, v0
	v_and_b32_e32 v3, 0xfffff807, v0
	v_and_b32_e32 v1, 0x700, v1
	v_and_b32_e32 v2, 0xf8, v2
	v_or3_b32 v1, v1, v3, v2
	v_cndmask_b32_e32 v52, v0, v1, vcc
	v_ashrrev_i32_e32 v53, 31, v52
	v_lshlrev_b64 v[0:1], 12, v[52:53]
	v_lshl_add_u64 v[0:1], v[50:51], 0, v[0:1]
	global_load_dwordx4 v[12:15], v[0:1], off
	global_load_dwordx4 v[8:11], v[0:1], off offset:1024
	global_load_dwordx4 v[4:7], v[0:1], off offset:2048
	s_nop 0
	global_load_dwordx4 v[0:3], v[0:1], off offset:3072
	s_waitcnt lgkmcnt(0)
	v_and_b32_e32 v70, 0xfffff807, v58
	v_and_b32_e32 v69, 0xf8, v69
	v_or3_b32 v59, v59, v70, v69
	v_cndmask_b32_e32 v58, v58, v59, vcc
	v_ashrrev_i32_e32 v59, 31, v58
	v_lshlrev_b64 v[70:71], 12, v[58:59]
	v_lshl_add_u64 v[70:71], v[50:51], 0, v[70:71]
	global_load_dwordx4 v[76:79], v[70:71], off
	global_load_dwordx4 v[80:83], v[70:71], off offset:1024
	global_load_dwordx4 v[84:87], v[70:71], off offset:2048
	global_load_dwordx4 v[88:91], v[70:71], off offset:3072
	v_lshlrev_b64 v[58:59], 11, v[58:59]
	v_lshl_add_u64 v[58:59], v[48:49], 0, v[58:59]
	s_waitcnt vmcnt(15)
	v_pk_mul_f32 v[70:71], v[44:45], v[44:45]
	s_waitcnt vmcnt(14)
	v_pk_mul_f32 v[74:75], v[40:41], v[40:41]
	v_pk_mul_f32 v[72:73], v[46:47], v[46:47]
	v_pk_mul_f32 v[92:93], v[42:43], v[42:43]
	s_waitcnt vmcnt(13)
	v_pk_mul_f32 v[94:95], v[36:37], v[36:37]
	v_add_f32_e32 v69, v74, v75
	v_add_f32_e32 v110, v70, v71
	v_pk_mul_f32 v[96:97], v[38:39], v[38:39]
	s_waitcnt vmcnt(12)
	v_pk_mul_f32 v[98:99], v[32:33], v[32:33]
	v_add_f32_e32 v111, v94, v95
	v_add_f32_e32 v69, v69, v92
	v_add_f32_e32 v72, v110, v72
	v_pk_mul_f32 v[100:101], v[34:35], v[34:35]
	v_add_f32_e32 v112, v98, v99
	v_add_f32_e32 v92, v111, v96
	v_add_f32_e32 v69, v69, v93
	v_add_f32_e32 v72, v72, v73
	v_add_f32_e32 v96, v112, v100
	v_add_f32_e32 v73, v92, v97
	v_add_f32_e32 v69, v72, v69
	v_add_f32_e32 v92, v96, v101
	v_add_f32_e32 v69, v69, v73
	s_waitcnt vmcnt(11)
	v_pk_mul_f32 v[70:71], v[28:29], v[28:29]
	s_waitcnt vmcnt(9)
	v_pk_mul_f32 v[102:103], v[20:21], v[20:21]
	v_add_f32_e32 v69, v69, v92
	v_add_f32_e32 v70, v70, v71
	v_add_f32_e32 v71, v102, v103
	ds_bpermute_b32 v103, v60, v69
	v_pk_mul_f32 v[74:75], v[30:31], v[30:31]
	v_pk_mul_f32 v[94:95], v[24:25], v[24:25]
	v_pk_mul_f32 v[98:99], v[26:27], v[26:27]
	v_add_f32_e32 v94, v94, v95
	v_add_f32_e32 v70, v70, v74
	v_pk_mul_f32 v[104:105], v[22:23], v[22:23]
	v_add_f32_e32 v72, v94, v98
	v_add_f32_e32 v70, v70, v75
	s_waitcnt vmcnt(6)
	v_pk_mul_f32 v[74:75], v[8:9], v[8:9]
	s_waitcnt lgkmcnt(0)
	v_add_f32_e32 v69, v69, v103
	v_add_f32_e32 v72, v72, v99
	v_add_f32_e32 v71, v71, v104
	v_add_f32_e32 v74, v74, v75
	ds_bpermute_b32 v75, v61, v69
	v_pk_mul_f32 v[106:107], v[16:17], v[16:17]
	v_add_f32_e32 v70, v70, v72
	v_add_f32_e32 v71, v71, v105
	v_pk_mul_f32 v[108:109], v[18:19], v[18:19]
	v_add_f32_e32 v70, v70, v71
	v_add_f32_e32 v71, v106, v107
	v_add_f32_e32 v71, v71, v108
	v_add_f32_e32 v71, v71, v109
	v_add_f32_e32 v102, v70, v71
	v_pk_mul_f32 v[70:71], v[12:13], v[12:13]
	s_waitcnt lgkmcnt(0)
	v_add_f32_e32 v69, v69, v75
	v_add_f32_e32 v70, v70, v71
	ds_bpermute_b32 v71, v62, v69
	v_pk_mul_f32 v[72:73], v[14:15], v[14:15]
	v_pk_mul_f32 v[92:93], v[10:11], v[10:11]
	s_waitcnt vmcnt(5)
	v_pk_mul_f32 v[94:95], v[4:5], v[4:5]
	v_pk_mul_f32 v[96:97], v[6:7], v[6:7]
	s_waitcnt lgkmcnt(0)
	v_add_f32_e32 v69, v69, v71
	v_add_f32_e32 v74, v74, v92
	v_add_f32_e32 v70, v70, v72
	v_add_f32_e32 v72, v94, v95
	ds_bpermute_b32 v71, v63, v69
	v_add_f32_e32 v74, v74, v93
	v_add_f32_e32 v70, v70, v73
	v_add_f32_e32 v72, v72, v96
	s_waitcnt vmcnt(4)
	v_pk_mul_f32 v[98:99], v[0:1], v[0:1]
	v_add_f32_e32 v70, v70, v74
	v_add_f32_e32 v72, v72, v97
	v_pk_mul_f32 v[100:101], v[2:3], v[2:3]
	v_add_f32_e32 v96, v70, v72
	v_add_f32_e32 v70, v98, v99
	s_waitcnt vmcnt(3)
	v_mov_b32_e32 v92, v77
	s_waitcnt vmcnt(2)
	v_mov_b32_e32 v93, v81
	v_add_f32_e32 v70, v70, v100
	v_mov_b32_e32 v74, v76
	v_mov_b32_e32 v75, v80
	v_pk_mul_f32 v[92:93], v[92:93], v[92:93]
	v_add_f32_e32 v97, v70, v101
	s_waitcnt lgkmcnt(0)
	v_add_f32_e32 v69, v69, v71
	v_mov_b32_e32 v70, v78
	v_mov_b32_e32 v71, v82
	v_pk_fma_f32 v[74:75], v[74:75], v[74:75], v[92:93]
	s_waitcnt vmcnt(1)
	v_mov_b32_e32 v94, v85
	s_waitcnt vmcnt(0)
	v_mov_b32_e32 v95, v89
	v_mov_b32_e32 v72, v79
	v_mov_b32_e32 v73, v83
	v_pk_fma_f32 v[70:71], v[70:71], v[70:71], v[74:75]
	v_mov_b32_e32 v92, v84
	v_mov_b32_e32 v93, v88
	v_pk_mul_f32 v[94:95], v[94:95], v[94:95]
	v_pk_fma_f32 v[70:71], v[72:73], v[72:73], v[70:71]
	v_mov_b32_e32 v72, v86
	v_mov_b32_e32 v73, v90
	v_pk_fma_f32 v[92:93], v[92:93], v[92:93], v[94:95]
	v_mov_b32_e32 v74, v87
	v_mov_b32_e32 v75, v91
	v_pk_fma_f32 v[72:73], v[72:73], v[72:73], v[92:93]
	v_add_f32_e32 v70, v70, v71
	v_pk_fma_f32 v[72:73], v[74:75], v[74:75], v[72:73]
	ds_bpermute_b32 v74, v60, v102
	v_add_f32_e32 v70, v70, v72
	v_add_f32_e32 v70, v70, v73
	ds_bpermute_b32 v71, v60, v70
	ds_bpermute_b32 v98, v64, v69
	s_waitcnt lgkmcnt(2)
	v_add_f32_e32 v74, v102, v74
	ds_bpermute_b32 v75, v61, v74
	v_add_f32_e32 v72, v96, v97
	s_waitcnt lgkmcnt(2)
	v_add_f32_e32 v70, v70, v71
	ds_bpermute_b32 v71, v61, v70
	s_waitcnt lgkmcnt(2)
	v_add_f32_e32 v73, v69, v98
	ds_bpermute_b32 v69, v60, v72
	s_waitcnt lgkmcnt(2)
	v_add_f32_e32 v74, v74, v75
	ds_bpermute_b32 v75, v62, v74
	s_waitcnt lgkmcnt(2)
	v_add_f32_e32 v70, v70, v71
	ds_bpermute_b32 v71, v62, v70
	s_waitcnt lgkmcnt(2)
	v_add_f32_e32 v69, v72, v69
	ds_bpermute_b32 v72, v61, v69
	s_waitcnt lgkmcnt(2)
	v_add_f32_e32 v74, v74, v75
	ds_bpermute_b32 v75, v63, v74
	s_waitcnt lgkmcnt(2)
	v_add_f32_e32 v70, v70, v71
	ds_bpermute_b32 v71, v63, v70
	s_waitcnt lgkmcnt(2)
	v_add_f32_e32 v69, v69, v72
	ds_bpermute_b32 v72, v62, v69
	s_waitcnt lgkmcnt(2)
	v_add_f32_e32 v75, v74, v75
	ds_bpermute_b32 v92, v64, v75
	s_waitcnt lgkmcnt(2)
	v_add_f32_e32 v70, v70, v71
	ds_bpermute_b32 v71, v64, v70
	s_waitcnt lgkmcnt(2)
	v_add_f32_e32 v69, v69, v72
	ds_bpermute_b32 v72, v63, v69
	ds_bpermute_b32 v74, v65, v73
	s_waitcnt lgkmcnt(2)
	v_add_f32_e32 v70, v70, v71
	ds_bpermute_b32 v94, v65, v70
	v_add_f32_e32 v71, v75, v92
	s_waitcnt lgkmcnt(2)
	v_add_f32_e32 v69, v69, v72
	ds_bpermute_b32 v93, v64, v69
	ds_bpermute_b32 v72, v65, v71
	s_waitcnt lgkmcnt(2)
	v_add_f32_e32 v70, v70, v94
	v_fmamk_f32 v70, v70, 0x3a800000, v67
	v_mul_f32_e32 v75, 0x4b800000, v70
	v_cmp_gt_f32_e64 s[8:9], s18, v70
	s_waitcnt lgkmcnt(1)
	v_add_f32_e32 v69, v69, v93
	v_cndmask_b32_e64 v70, v70, v75, s[8:9]
	v_rsq_f32_e32 v75, v70
	ds_bpermute_b32 v70, v65, v69
	v_mul_f32_e32 v92, 0x45800000, v75
	v_cndmask_b32_e64 v92, v75, v92, s[8:9]
	v_pk_mul_f32 v[76:77], v[76:77], v[92:93] op_sel_hi:[1,0]
	v_pk_mul_f32 v[78:79], v[78:79], v[92:93] op_sel_hi:[1,0]
	v_cvt_pk_bf16_f32 v76, v76, v77
	v_cvt_pk_bf16_f32 v77, v78, v79
	global_store_dwordx2 v[58:59], v[76:77], off sc1
	v_pk_mul_f32 v[76:77], v[80:81], v[92:93] op_sel_hi:[1,0]
	v_pk_mul_f32 v[78:79], v[82:83], v[92:93] op_sel_hi:[1,0]
	v_cvt_pk_bf16_f32 v76, v76, v77
	v_cvt_pk_bf16_f32 v77, v78, v79
	global_store_dwordx2 v[58:59], v[76:77], off offset:512 sc1
	v_pk_mul_f32 v[76:77], v[84:85], v[92:93] op_sel_hi:[1,0]
	v_pk_mul_f32 v[78:79], v[86:87], v[92:93] op_sel_hi:[1,0]
	v_cvt_pk_bf16_f32 v76, v76, v77
	v_cvt_pk_bf16_f32 v77, v78, v79
	global_store_dwordx2 v[58:59], v[76:77], off offset:1024 sc1
	v_pk_mul_f32 v[76:77], v[88:89], v[92:93] op_sel_hi:[1,0]
	v_pk_mul_f32 v[78:79], v[90:91], v[92:93] op_sel_hi:[1,0]
	v_cvt_pk_bf16_f32 v76, v76, v77
	v_cvt_pk_bf16_f32 v77, v78, v79
	global_store_dwordx2 v[58:59], v[76:77], off offset:1536 sc1
	s_and_saveexec_b64 s[8:9], s[6:7]
	s_cbranch_execnz .LBB0_871
	s_or_b64 exec, exec, s[8:9]
	s_and_saveexec_b64 s[6:7], s[0:1]
	s_cbranch_execnz .LBB0_872

.LBB0_871:
	v_add_f32_e32 v58, v73, v74
	v_fmamk_f32 v58, v58, 0x3a800000, v67
	v_mul_f32_e32 v59, 0x4b800000, v58
	v_cmp_gt_f32_e64 s[6:7], s18, v58
	v_lshlrev_b64 v[56:57], 11, v[56:57]
	s_nop 0
	v_cndmask_b32_e64 v58, v58, v59, s[6:7]
	v_rsq_f32_e32 v58, v58
	s_nop 0
	v_mul_f32_e32 v59, 0x45800000, v58
	v_cndmask_b32_e64 v58, v58, v59, s[6:7]
	v_pk_mul_f32 v[44:45], v[44:45], v[58:59] op_sel_hi:[1,0]
	v_pk_mul_f32 v[46:47], v[46:47], v[58:59] op_sel_hi:[1,0]
	v_pk_mul_f32 v[40:41], v[40:41], v[58:59] op_sel_hi:[1,0]
	v_pk_mul_f32 v[42:43], v[42:43], v[58:59] op_sel_hi:[1,0]
	v_pk_mul_f32 v[36:37], v[36:37], v[58:59] op_sel_hi:[1,0]
	v_pk_mul_f32 v[38:39], v[38:39], v[58:59] op_sel_hi:[1,0]
	v_pk_mul_f32 v[32:33], v[32:33], v[58:59] op_sel_hi:[1,0]
	v_pk_mul_f32 v[34:35], v[34:35], v[58:59] op_sel_hi:[1,0]
	v_cvt_pk_bf16_f32 v44, v44, v45
	v_cvt_pk_bf16_f32 v45, v46, v47
	v_lshl_add_u64 v[46:47], v[48:49], 0, v[56:57]
	v_cvt_pk_bf16_f32 v40, v40, v41
	v_cvt_pk_bf16_f32 v41, v42, v43
	v_cvt_pk_bf16_f32 v36, v36, v37
	v_cvt_pk_bf16_f32 v37, v38, v39
	v_cvt_pk_bf16_f32 v32, v32, v33
	v_cvt_pk_bf16_f32 v33, v34, v35
	global_store_dwordx2 v[46:47], v[44:45], off sc1
	global_store_dwordx2 v[46:47], v[40:41], off offset:512 sc1
	global_store_dwordx2 v[46:47], v[36:37], off offset:1024 sc1
	global_store_dwordx2 v[46:47], v[32:33], off offset:1536 sc1
	s_or_b64 exec, exec, s[8:9]
	s_and_saveexec_b64 s[6:7], s[0:1]
	s_cbranch_execz .LBB0_870
.LBB0_872:
	s_waitcnt lgkmcnt(1)
	v_add_f32_e32 v32, v71, v72
	v_fmamk_f32 v32, v32, 0x3a800000, v67
	v_mul_f32_e32 v33, 0x4b800000, v32
	v_cmp_gt_f32_e64 s[0:1], s18, v32
	s_nop 1
	v_cndmask_b32_e64 v32, v32, v33, s[0:1]
	v_rsq_f32_e32 v34, v32
	v_lshlrev_b64 v[32:33], 11, v[54:55]
	v_mul_f32_e32 v35, 0x45800000, v34
	v_cndmask_b32_e64 v34, v34, v35, s[0:1]
	v_pk_mul_f32 v[28:29], v[28:29], v[34:35] op_sel_hi:[1,0]
	v_pk_mul_f32 v[30:31], v[30:31], v[34:35] op_sel_hi:[1,0]
	v_pk_mul_f32 v[24:25], v[24:25], v[34:35] op_sel_hi:[1,0]
	v_pk_mul_f32 v[26:27], v[26:27], v[34:35] op_sel_hi:[1,0]
	v_pk_mul_f32 v[20:21], v[20:21], v[34:35] op_sel_hi:[1,0]
	v_pk_mul_f32 v[22:23], v[22:23], v[34:35] op_sel_hi:[1,0]
	v_pk_mul_f32 v[16:17], v[16:17], v[34:35] op_sel_hi:[1,0]
	v_pk_mul_f32 v[18:19], v[18:19], v[34:35] op_sel_hi:[1,0]
	v_cvt_pk_bf16_f32 v28, v28, v29
	v_cvt_pk_bf16_f32 v29, v30, v31
	v_lshl_add_u64 v[30:31], v[48:49], 0, v[32:33]
	v_cvt_pk_bf16_f32 v24, v24, v25
	v_cvt_pk_bf16_f32 v25, v26, v27
	v_cvt_pk_bf16_f32 v20, v20, v21
	v_cvt_pk_bf16_f32 v21, v22, v23
	v_cvt_pk_bf16_f32 v16, v16, v17
	v_cvt_pk_bf16_f32 v17, v18, v19
	global_store_dwordx2 v[30:31], v[28:29], off sc1
	global_store_dwordx2 v[30:31], v[24:25], off offset:512 sc1
	global_store_dwordx2 v[30:31], v[20:21], off offset:1024 sc1
	global_store_dwordx2 v[30:31], v[16:17], off offset:1536 sc1
	s_or_b64 exec, exec, s[6:7]
	s_and_saveexec_b64 s[6:7], s[4:5]
	s_cbranch_execz .LBB0_867
.LBB0_873:
	s_waitcnt lgkmcnt(0)
	v_add_f32_e32 v16, v69, v70
	v_fmamk_f32 v16, v16, 0x3a800000, v67
	v_mul_f32_e32 v17, 0x4b800000, v16
	v_cmp_gt_f32_e64 s[0:1], s18, v16
	s_nop 1
	v_cndmask_b32_e64 v16, v16, v17, s[0:1]
	v_rsq_f32_e32 v18, v16
	v_lshlrev_b64 v[16:17], 11, v[52:53]
	v_mul_f32_e32 v19, 0x45800000, v18
	v_cndmask_b32_e64 v18, v18, v19, s[0:1]
	v_pk_mul_f32 v[12:13], v[12:13], v[18:19] op_sel_hi:[1,0]
	v_pk_mul_f32 v[14:15], v[14:15], v[18:19] op_sel_hi:[1,0]
	v_pk_mul_f32 v[8:9], v[8:9], v[18:19] op_sel_hi:[1,0]
	v_pk_mul_f32 v[10:11], v[10:11], v[18:19] op_sel_hi:[1,0]
	v_pk_mul_f32 v[4:5], v[4:5], v[18:19] op_sel_hi:[1,0]
	v_pk_mul_f32 v[6:7], v[6:7], v[18:19] op_sel_hi:[1,0]
	v_pk_mul_f32 v[0:1], v[0:1], v[18:19] op_sel_hi:[1,0]
	v_pk_mul_f32 v[2:3], v[2:3], v[18:19] op_sel_hi:[1,0]
	v_cvt_pk_bf16_f32 v12, v12, v13
	v_cvt_pk_bf16_f32 v13, v14, v15
	v_lshl_add_u64 v[14:15], v[48:49], 0, v[16:17]
	v_cvt_pk_bf16_f32 v8, v8, v9
	v_cvt_pk_bf16_f32 v9, v10, v11
	v_cvt_pk_bf16_f32 v4, v4, v5
	v_cvt_pk_bf16_f32 v5, v6, v7
	v_cvt_pk_bf16_f32 v0, v0, v1
	v_cvt_pk_bf16_f32 v1, v2, v3
	global_store_dwordx2 v[14:15], v[12:13], off sc1
	global_store_dwordx2 v[14:15], v[8:9], off offset:512 sc1
	global_store_dwordx2 v[14:15], v[4:5], off offset:1024 sc1
	global_store_dwordx2 v[14:15], v[0:1], off offset:1536 sc1
	s_branch .LBB0_867

.LBB0_1423:
	v_add_u32_e32 v0, s16, v58
	v_cmp_gt_i32_e64 s[6:7], s3, v0
	v_lshrrev_b32_e32 v69, 3, v58
	v_and_b32_e32 v59, 0x700, v66
	v_cndmask_b32_e64 v1, v58, v0, s[6:7]
	v_lshlrev_b32_e32 v2, 5, v1
	v_lshrrev_b32_e32 v3, 3, v1
	v_and_b32_e32 v2, 0x700, v2
	v_and_b32_e32 v3, 0xf8, v3
	v_and_b32_e32 v4, 0xfffff807, v1
	v_or3_b32 v2, v2, v4, v3
	v_cndmask_b32_e32 v56, v1, v2, vcc
	v_add_u32_e32 v2, s16, v0
	v_cmp_gt_i32_e64 s[0:1], s3, v2
	v_ashrrev_i32_e32 v57, 31, v56
	v_add_u32_e32 v68, s16, v2
	v_cndmask_b32_e64 v3, v58, v2, s[0:1]
	v_lshlrev_b32_e32 v0, 5, v3
	v_and_b32_e32 v4, 0x700, v0
	v_lshlrev_b64 v[0:1], 12, v[56:57]
	v_lshl_add_u64 v[0:1], v[50:51], 0, v[0:1]
	v_lshrrev_b32_e32 v5, 3, v3
	global_load_dwordx4 v[44:47], v[0:1], off
	global_load_dwordx4 v[40:43], v[0:1], off offset:1024
	v_and_b32_e32 v5, 0xf8, v5
	v_and_b32_e32 v6, 0xfffff807, v3
	global_load_dwordx4 v[36:39], v[0:1], off offset:2048
	global_load_dwordx4 v[32:35], v[0:1], off offset:3072
	v_or3_b32 v0, v4, v6, v5
	v_cndmask_b32_e32 v54, v3, v0, vcc
	v_ashrrev_i32_e32 v55, 31, v54
	v_lshlrev_b64 v[0:1], 12, v[54:55]
	v_lshl_add_u64 v[0:1], v[50:51], 0, v[0:1]
	v_cmp_gt_i32_e64 s[4:5], s3, v68
	global_load_dwordx4 v[28:31], v[0:1], off
	global_load_dwordx4 v[24:27], v[0:1], off offset:1024
	global_load_dwordx4 v[20:23], v[0:1], off offset:2048
	global_load_dwordx4 v[16:19], v[0:1], off offset:3072
	v_cndmask_b32_e64 v0, v58, v68, s[4:5]
	v_lshlrev_b32_e32 v1, 5, v0
	v_lshrrev_b32_e32 v2, 3, v0
	v_and_b32_e32 v3, 0xfffff807, v0
	v_and_b32_e32 v1, 0x700, v1
	v_and_b32_e32 v2, 0xf8, v2
	v_or3_b32 v1, v1, v3, v2
	v_cndmask_b32_e32 v52, v0, v1, vcc
	v_ashrrev_i32_e32 v53, 31, v52
	v_lshlrev_b64 v[0:1], 12, v[52:53]
	s_waitcnt lgkmcnt(0)
	v_lshl_add_u64 v[70:71], v[50:51], 0, v[0:1]
	global_load_dwordx4 v[12:15], v[70:71], off
	global_load_dwordx4 v[8:11], v[70:71], off offset:1024
	global_load_dwordx4 v[4:7], v[70:71], off offset:2048
	global_load_dwordx4 v[0:3], v[70:71], off offset:3072
	v_and_b32_e32 v70, 0xfffff807, v58
	v_and_b32_e32 v69, 0xf8, v69
	v_or3_b32 v59, v59, v70, v69
	v_cndmask_b32_e32 v58, v58, v59, vcc
	v_ashrrev_i32_e32 v59, 31, v58
	v_lshlrev_b64 v[70:71], 12, v[58:59]
	v_lshl_add_u64 v[70:71], v[50:51], 0, v[70:71]
	global_load_dwordx4 v[76:79], v[70:71], off
	global_load_dwordx4 v[80:83], v[70:71], off offset:1024
	global_load_dwordx4 v[84:87], v[70:71], off offset:2048
	global_load_dwordx4 v[88:91], v[70:71], off offset:3072
	v_lshlrev_b64 v[58:59], 11, v[58:59]
	v_lshl_add_u64 v[58:59], v[48:49], 0, v[58:59]
	s_waitcnt vmcnt(15)
	v_pk_mul_f32 v[70:71], v[44:45], v[44:45]
	s_waitcnt vmcnt(14)
	v_pk_mul_f32 v[74:75], v[40:41], v[40:41]
	v_pk_mul_f32 v[72:73], v[46:47], v[46:47]
	v_pk_mul_f32 v[92:93], v[42:43], v[42:43]
	s_waitcnt vmcnt(13)
	v_pk_mul_f32 v[94:95], v[36:37], v[36:37]
	v_add_f32_e32 v69, v74, v75
	v_add_f32_e32 v110, v70, v71
	v_pk_mul_f32 v[96:97], v[38:39], v[38:39]
	s_waitcnt vmcnt(12)
	v_pk_mul_f32 v[98:99], v[32:33], v[32:33]
	v_add_f32_e32 v111, v94, v95
	v_add_f32_e32 v69, v69, v92
	v_add_f32_e32 v72, v110, v72
	v_pk_mul_f32 v[100:101], v[34:35], v[34:35]
	v_add_f32_e32 v112, v98, v99
	v_add_f32_e32 v92, v111, v96
	v_add_f32_e32 v69, v69, v93
	v_add_f32_e32 v72, v72, v73
	v_add_f32_e32 v96, v112, v100
	v_add_f32_e32 v73, v92, v97
	v_add_f32_e32 v69, v72, v69
	v_add_f32_e32 v92, v96, v101
	v_add_f32_e32 v69, v69, v73
	s_waitcnt vmcnt(11)
	v_pk_mul_f32 v[70:71], v[28:29], v[28:29]
	s_waitcnt vmcnt(9)
	v_pk_mul_f32 v[102:103], v[20:21], v[20:21]
	v_add_f32_e32 v69, v69, v92
	v_add_f32_e32 v70, v70, v71
	v_add_f32_e32 v71, v102, v103
	ds_bpermute_b32 v103, v60, v69
	v_pk_mul_f32 v[74:75], v[30:31], v[30:31]
	v_pk_mul_f32 v[94:95], v[24:25], v[24:25]
	v_pk_mul_f32 v[98:99], v[26:27], v[26:27]
	v_add_f32_e32 v94, v94, v95
	v_add_f32_e32 v70, v70, v74
	v_pk_mul_f32 v[104:105], v[22:23], v[22:23]
	v_add_f32_e32 v72, v94, v98
	v_add_f32_e32 v70, v70, v75
	s_waitcnt vmcnt(6)
	v_pk_mul_f32 v[74:75], v[8:9], v[8:9]
	s_waitcnt lgkmcnt(0)
	v_add_f32_e32 v69, v69, v103
	v_add_f32_e32 v72, v72, v99
	v_add_f32_e32 v71, v71, v104
	v_add_f32_e32 v74, v74, v75
	ds_bpermute_b32 v75, v61, v69
	v_pk_mul_f32 v[106:107], v[16:17], v[16:17]
	v_add_f32_e32 v70, v70, v72
	v_add_f32_e32 v71, v71, v105
	v_pk_mul_f32 v[108:109], v[18:19], v[18:19]
	v_add_f32_e32 v70, v70, v71
	v_add_f32_e32 v71, v106, v107
	v_add_f32_e32 v71, v71, v108
	v_add_f32_e32 v71, v71, v109
	v_add_f32_e32 v102, v70, v71
	v_pk_mul_f32 v[70:71], v[12:13], v[12:13]
	s_waitcnt lgkmcnt(0)
	v_add_f32_e32 v69, v69, v75
	v_add_f32_e32 v70, v70, v71
	ds_bpermute_b32 v71, v62, v69
	v_pk_mul_f32 v[72:73], v[14:15], v[14:15]
	v_pk_mul_f32 v[92:93], v[10:11], v[10:11]
	s_waitcnt vmcnt(5)
	v_pk_mul_f32 v[94:95], v[4:5], v[4:5]
	v_pk_mul_f32 v[96:97], v[6:7], v[6:7]
	s_waitcnt lgkmcnt(0)
	v_add_f32_e32 v69, v69, v71
	v_add_f32_e32 v74, v74, v92
	v_add_f32_e32 v70, v70, v72
	v_add_f32_e32 v72, v94, v95
	ds_bpermute_b32 v71, v63, v69
	v_add_f32_e32 v74, v74, v93
	v_add_f32_e32 v70, v70, v73
	v_add_f32_e32 v72, v72, v96
	s_waitcnt vmcnt(4)
	v_pk_mul_f32 v[98:99], v[0:1], v[0:1]
	v_add_f32_e32 v70, v70, v74
	v_add_f32_e32 v72, v72, v97
	v_pk_mul_f32 v[100:101], v[2:3], v[2:3]
	v_add_f32_e32 v96, v70, v72
	v_add_f32_e32 v70, v98, v99
	s_waitcnt vmcnt(3)
	v_mov_b32_e32 v92, v77
	s_waitcnt vmcnt(2)
	v_mov_b32_e32 v93, v81
	v_add_f32_e32 v70, v70, v100
	v_mov_b32_e32 v74, v76
	v_mov_b32_e32 v75, v80
	v_pk_mul_f32 v[92:93], v[92:93], v[92:93]
	v_add_f32_e32 v97, v70, v101
	s_waitcnt lgkmcnt(0)
	v_add_f32_e32 v69, v69, v71
	v_mov_b32_e32 v70, v78
	v_mov_b32_e32 v71, v82
	v_pk_fma_f32 v[74:75], v[74:75], v[74:75], v[92:93]
	s_waitcnt vmcnt(1)
	v_mov_b32_e32 v94, v85
	s_waitcnt vmcnt(0)
	v_mov_b32_e32 v95, v89
	v_mov_b32_e32 v72, v79
	v_mov_b32_e32 v73, v83
	v_pk_fma_f32 v[70:71], v[70:71], v[70:71], v[74:75]
	v_mov_b32_e32 v92, v84
	v_mov_b32_e32 v93, v88
	v_pk_mul_f32 v[94:95], v[94:95], v[94:95]
	v_pk_fma_f32 v[70:71], v[72:73], v[72:73], v[70:71]
	v_mov_b32_e32 v72, v86
	v_mov_b32_e32 v73, v90
	v_pk_fma_f32 v[92:93], v[92:93], v[92:93], v[94:95]
	v_mov_b32_e32 v74, v87
	v_mov_b32_e32 v75, v91
	v_pk_fma_f32 v[72:73], v[72:73], v[72:73], v[92:93]
	v_add_f32_e32 v70, v70, v71
	v_pk_fma_f32 v[72:73], v[74:75], v[74:75], v[72:73]
	ds_bpermute_b32 v74, v60, v102
	v_add_f32_e32 v70, v70, v72
	v_add_f32_e32 v70, v70, v73
	ds_bpermute_b32 v71, v60, v70
	ds_bpermute_b32 v98, v64, v69
	s_waitcnt lgkmcnt(2)
	v_add_f32_e32 v74, v102, v74
	ds_bpermute_b32 v75, v61, v74
	v_add_f32_e32 v72, v96, v97
	s_waitcnt lgkmcnt(2)
	v_add_f32_e32 v70, v70, v71
	ds_bpermute_b32 v71, v61, v70
	s_waitcnt lgkmcnt(2)
	v_add_f32_e32 v73, v69, v98
	ds_bpermute_b32 v69, v60, v72
	s_waitcnt lgkmcnt(2)
	v_add_f32_e32 v74, v74, v75
	ds_bpermute_b32 v75, v62, v74
	s_waitcnt lgkmcnt(2)
	v_add_f32_e32 v70, v70, v71
	ds_bpermute_b32 v71, v62, v70
	s_waitcnt lgkmcnt(2)
	v_add_f32_e32 v69, v72, v69
	ds_bpermute_b32 v72, v61, v69
	s_waitcnt lgkmcnt(2)
	v_add_f32_e32 v74, v74, v75
	ds_bpermute_b32 v75, v63, v74
	s_waitcnt lgkmcnt(2)
	v_add_f32_e32 v70, v70, v71
	ds_bpermute_b32 v71, v63, v70
	s_waitcnt lgkmcnt(2)
	v_add_f32_e32 v69, v69, v72
	ds_bpermute_b32 v72, v62, v69
	s_waitcnt lgkmcnt(2)
	v_add_f32_e32 v75, v74, v75
	ds_bpermute_b32 v92, v64, v75
	s_waitcnt lgkmcnt(2)
	v_add_f32_e32 v70, v70, v71
	ds_bpermute_b32 v71, v64, v70
	s_waitcnt lgkmcnt(2)
	v_add_f32_e32 v69, v69, v72
	ds_bpermute_b32 v72, v63, v69
	ds_bpermute_b32 v74, v65, v73
	s_waitcnt lgkmcnt(2)
	v_add_f32_e32 v70, v70, v71
	ds_bpermute_b32 v94, v65, v70
	v_add_f32_e32 v71, v75, v92
	s_waitcnt lgkmcnt(2)
	v_add_f32_e32 v69, v69, v72
	ds_bpermute_b32 v93, v64, v69
	ds_bpermute_b32 v72, v65, v71
	s_waitcnt lgkmcnt(2)
	v_add_f32_e32 v70, v70, v94
	v_fmamk_f32 v70, v70, 0x3a800000, v67
	v_mul_f32_e32 v75, 0x4b800000, v70
	v_cmp_gt_f32_e64 s[8:9], s18, v70
	s_waitcnt lgkmcnt(1)
	v_add_f32_e32 v69, v69, v93
	v_cndmask_b32_e64 v70, v70, v75, s[8:9]
	v_rsq_f32_e32 v75, v70
	ds_bpermute_b32 v70, v65, v69
	v_mul_f32_e32 v92, 0x45800000, v75
	v_cndmask_b32_e64 v92, v75, v92, s[8:9]
	v_pk_mul_f32 v[76:77], v[76:77], v[92:93] op_sel_hi:[1,0]
	v_pk_mul_f32 v[78:79], v[78:79], v[92:93] op_sel_hi:[1,0]
	v_cvt_pk_bf16_f32 v76, v76, v77
	v_cvt_pk_bf16_f32 v77, v78, v79
	global_store_dwordx2 v[58:59], v[76:77], off sc1
	v_pk_mul_f32 v[76:77], v[80:81], v[92:93] op_sel_hi:[1,0]
	v_pk_mul_f32 v[78:79], v[82:83], v[92:93] op_sel_hi:[1,0]
	v_cvt_pk_bf16_f32 v76, v76, v77
	v_cvt_pk_bf16_f32 v77, v78, v79
	global_store_dwordx2 v[58:59], v[76:77], off offset:512 sc1
	v_pk_mul_f32 v[76:77], v[84:85], v[92:93] op_sel_hi:[1,0]
	v_pk_mul_f32 v[78:79], v[86:87], v[92:93] op_sel_hi:[1,0]
	v_cvt_pk_bf16_f32 v76, v76, v77
	v_cvt_pk_bf16_f32 v77, v78, v79
	global_store_dwordx2 v[58:59], v[76:77], off offset:1024 sc1
	v_pk_mul_f32 v[76:77], v[88:89], v[92:93] op_sel_hi:[1,0]
	v_pk_mul_f32 v[78:79], v[90:91], v[92:93] op_sel_hi:[1,0]
	v_cvt_pk_bf16_f32 v76, v76, v77
	v_cvt_pk_bf16_f32 v77, v78, v79
	global_store_dwordx2 v[58:59], v[76:77], off offset:1536 sc1
	s_and_saveexec_b64 s[8:9], s[6:7]
	s_cbranch_execnz .LBB0_1426
	s_or_b64 exec, exec, s[8:9]
	s_and_saveexec_b64 s[6:7], s[0:1]
	s_cbranch_execnz .LBB0_1427
